# GEMM1 task order m-tile fastest (one XCD's blocks share 17 m-tiles and the ~4 concurrent weight tiles), ml_k2 second-k-step fragment reads issued together
# speedup vs baseline: 1.0219x; 1.0088x over previous
.LBB0_465:
	s_waitcnt vmcnt(18)
	v_mov_b32_e32 v138, v119
	v_ashrrev_i32_e32 v119, 31, v118
	ds_write_b128 v133, v[2:5]
	ds_write_b128 v133, v[6:9] offset:9216
	ds_write_b128 v133, v[10:13] offset:18432
	ds_write_b128 v133, v[14:17] offset:27648
	ds_write_b128 v132, v[18:21]
	ds_write_b128 v132, v[22:25] offset:9216
	ds_write_b128 v132, v[26:29] offset:18432
	ds_write_b128 v132, v[30:33] offset:27648
	v_lshlrev_b64 v[2:3], 13, v[118:119]
	v_lshl_add_u64 v[2:3], s[30:31], 0, v[2:3]
	s_lshl_b32 s2, s41, 1
	v_lshl_add_u64 v[2:3], v[2:3], 0, s[2:3]
	v_lshl_add_u64 v[2:3], v[2:3], 0, v[0:1]
	v_add_co_u32_e32 v2, vcc, s93, v2
	v_lshl_add_u64 v[14:15], s[24:25], 0, v[112:113]
	s_nop 0
	v_addc_co_u32_e32 v3, vcc, 0, v3, vcc
	v_add_co_u32_e32 v6, vcc, s4, v14
	s_waitcnt vmcnt(16)
	v_mov_b32_e32 v121, v117
	v_addc_co_u32_e32 v7, vcc, 0, v15, vcc
	v_ashrrev_i32_e32 v117, 31, v116
	v_add_co_u32_e32 v10, vcc, s5, v14
	v_lshlrev_b64 v[18:19], 13, v[116:117]
	s_nop 0
	v_addc_co_u32_e32 v11, vcc, 0, v15, vcc
	v_lshl_add_u64 v[18:19], s[30:31], 0, v[18:19]
	v_add_co_u32_e32 v14, vcc, s6, v14
	v_lshl_add_u64 v[18:19], v[18:19], 0, s[2:3]
	s_nop 0
	v_addc_co_u32_e32 v15, vcc, 0, v15, vcc
	v_lshl_add_u64 v[18:19], v[18:19], 0, v[0:1]
	v_add_co_u32_e32 v18, vcc, s93, v18
	v_lshl_add_u64 v[30:31], s[24:25], 0, v[114:115]
	s_nop 0
	v_addc_co_u32_e32 v19, vcc, 0, v19, vcc
	v_add_co_u32_e32 v22, vcc, s4, v30
	v_lshl_add_u64 v[34:35], s[24:25], 0, v[110:111]
	s_nop 0
	v_addc_co_u32_e32 v23, vcc, 0, v31, vcc
	v_add_co_u32_e32 v26, vcc, s5, v30
	s_mov_b32 s44, 0x3000000
	s_nop 0
	v_addc_co_u32_e32 v27, vcc, 0, v31, vcc
	v_add_co_u32_e32 v30, vcc, s6, v30
	v_mov_b32_e32 v36, v134
	s_nop 0
	v_addc_co_u32_e32 v31, vcc, 0, v31, vcc
	v_add_co_u32_e32 v34, vcc, s44, v34
	v_mov_b32_e32 v66, v131
	s_nop 0
	v_addc_co_u32_e32 v35, vcc, 0, v35, vcc
	v_mov_b32_e32 v67, v130
	s_waitcnt lgkmcnt(0)
	s_barrier
	global_load_dwordx4 v[2:5], v[2:3], off offset:1552
	v_max_f32_e32 v139, v83, v83
	global_load_dwordx4 v[6:9], v[6:7], off
	s_add_u32 s44, s24, s42
	global_load_dwordx4 v[10:13], v[10:11], off
	v_mov_b32_e32 v120, v125
	global_load_dwordx4 v[14:17], v[14:15], off
	s_addc_u32 s45, s25, s43
	global_load_dwordx4 v[18:21], v[18:19], off offset:1552
	v_add_u32_e32 v136, 0x800, v127
	global_load_dwordx4 v[22:25], v[22:23], off
	v_add_u32_e32 v135, 0x1000, v127
	global_load_dwordx4 v[26:29], v[26:27], off
	v_add_u32_e32 v137, 0x1800, v127
	global_load_dwordx4 v[30:33], v[30:31], off
	s_nop 0
	global_load_dword v131, v[34:35], off offset:1280
	global_load_dword v134, v[34:35], off offset:1536
	global_load_dword v130, v[34:35], off offset:1792
	global_load_dword v119, v[34:35], off offset:2048
	v_max_f32_e32 v34, v36, v36
	v_max_f32_e32 v68, v139, v34
	v_sub_f32_e32 v34, v83, v68
	global_load_dword v125, v148, s[44:45] offset:2304
	global_load_dword v117, v148, s[44:45] offset:1532
	ds_write_b32 v128, v82 offset:36864
	v_mul_f32_e32 v69, 0x3fb8aa3b, v34
	v_sub_f32_e32 v34, v120, v68
	v_mul_f32_e32 v70, 0x3fb8aa3b, v34
	s_mov_b64 s[44:45], 0x500
	v_lshl_add_u64 v[110:111], v[110:111], 0, s[44:45]
	v_lshl_add_u64 v[112:113], v[112:113], 0, s[8:9]
	v_lshl_add_u64 v[114:115], v[114:115], 0, s[8:9]
	v_add_u32_e32 v116, 64, v116
	v_add_u32_e32 v118, 64, v118
	ds_read_b128 v[34:37], v107
	ds_read_b128 v[38:41], v129 offset:36864
	ds_read_b128 v[42:45], v129 offset:36880
	ds_read_b128 v[46:49], v107 offset:16
	ds_read_b128 v[50:53], v129 offset:36896
	ds_read_b128 v[54:57], v129 offset:36912
	ds_read_b128 v[58:61], v107 offset:32
	ds_read_b128 v[62:65], v129 offset:36928
	ds_read_b128 v[208:211], v129 offset:36944
	ds_read_b128 v[212:215], v107 offset:48
	ds_read_b128 v[216:219], v129 offset:36960
	ds_read_b128 v[220:223], v129 offset:36976
	ds_read_b128 v[224:227], v107 offset:64
	ds_read_b128 v[228:231], v129 offset:36992
	ds_read_b128 v[232:235], v129 offset:37008
	s_waitcnt lgkmcnt(9)
	v_and_b32_e32 v254, 0xffff0000, v34
	v_and_b32_e32 v236, 0xffff0000, v46
	v_mul_f32_e32 v252, v39, v254
	v_mul_f32_e32 v253, v51, v236
	v_lshlrev_b32_e32 v71, 16, v34
	v_lshlrev_b32_e32 v237, 16, v46
	v_fmac_f32_e32 v252, v38, v71
	v_fmac_f32_e32 v253, v50, v237
	v_lshlrev_b32_e32 v254, 16, v35
	v_lshlrev_b32_e32 v236, 16, v47
	v_fmac_f32_e32 v252, v40, v254
	v_fmac_f32_e32 v253, v52, v236
	v_and_b32_e32 v71, 0xffff0000, v35
	v_and_b32_e32 v237, 0xffff0000, v47
	v_fmac_f32_e32 v252, v41, v71
	v_fmac_f32_e32 v253, v53, v237
	v_lshlrev_b32_e32 v254, 16, v36
	v_lshlrev_b32_e32 v236, 16, v48
	v_fmac_f32_e32 v252, v42, v254
	v_fmac_f32_e32 v253, v54, v236
	v_and_b32_e32 v71, 0xffff0000, v36
	v_and_b32_e32 v237, 0xffff0000, v48
	v_fmac_f32_e32 v252, v43, v71
	v_fmac_f32_e32 v253, v55, v237
	v_lshlrev_b32_e32 v254, 16, v37
	v_lshlrev_b32_e32 v236, 16, v49
	v_fmac_f32_e32 v252, v44, v254
	v_fmac_f32_e32 v253, v56, v236
	v_and_b32_e32 v71, 0xffff0000, v37
	v_and_b32_e32 v237, 0xffff0000, v49
	v_fmac_f32_e32 v252, v45, v71
	v_fmac_f32_e32 v253, v57, v237
	v_add_f32_e32 v242, 0, v252
	v_add_f32_e32 v242, v242, v253
	ds_read_b128 v[34:37], v107 offset:80
	ds_read_b128 v[38:41], v129 offset:37024
	ds_read_b128 v[42:45], v129 offset:37040
	ds_read_b128 v[46:49], v107 offset:96
	ds_read_b128 v[50:53], v129 offset:37056
	ds_read_b128 v[54:57], v129 offset:37072
	s_waitcnt lgkmcnt(9)
	v_and_b32_e32 v254, 0xffff0000, v58
	v_and_b32_e32 v236, 0xffff0000, v212
	v_mul_f32_e32 v252, v63, v254
	v_mul_f32_e32 v253, v217, v236
	v_lshlrev_b32_e32 v71, 16, v58
	v_lshlrev_b32_e32 v237, 16, v212
	v_fmac_f32_e32 v252, v62, v71
	v_fmac_f32_e32 v253, v216, v237
	v_lshlrev_b32_e32 v254, 16, v59
	v_lshlrev_b32_e32 v236, 16, v213
	v_fmac_f32_e32 v252, v64, v254
	v_fmac_f32_e32 v253, v218, v236
	v_and_b32_e32 v71, 0xffff0000, v59
	v_and_b32_e32 v237, 0xffff0000, v213
	v_fmac_f32_e32 v252, v65, v71
	v_fmac_f32_e32 v253, v219, v237
	v_lshlrev_b32_e32 v254, 16, v60
	v_lshlrev_b32_e32 v236, 16, v214
	v_fmac_f32_e32 v252, v208, v254
	v_fmac_f32_e32 v253, v220, v236
	v_and_b32_e32 v71, 0xffff0000, v60
	v_and_b32_e32 v237, 0xffff0000, v214
	v_fmac_f32_e32 v252, v209, v71
	v_fmac_f32_e32 v253, v221, v237
	v_lshlrev_b32_e32 v254, 16, v61
	v_lshlrev_b32_e32 v236, 16, v215
	v_fmac_f32_e32 v252, v210, v254
	v_fmac_f32_e32 v253, v222, v236
	v_and_b32_e32 v71, 0xffff0000, v61
	v_and_b32_e32 v237, 0xffff0000, v215
	v_fmac_f32_e32 v252, v211, v71
	v_fmac_f32_e32 v253, v223, v237
	v_add_f32_e32 v242, v242, v252
	v_add_f32_e32 v242, v242, v253
	ds_read_b128 v[58:61], v107 offset:112
	ds_read_b128 v[62:65], v129 offset:37088
	ds_read_b128 v[208:211], v129 offset:37104
	s_waitcnt lgkmcnt(6)
	v_and_b32_e32 v254, 0xffff0000, v224
	v_and_b32_e32 v236, 0xffff0000, v34
	v_mul_f32_e32 v252, v229, v254
	v_mul_f32_e32 v253, v39, v236
	v_lshlrev_b32_e32 v71, 16, v224
	v_lshlrev_b32_e32 v237, 16, v34
	v_fmac_f32_e32 v252, v228, v71
	v_fmac_f32_e32 v253, v38, v237
	v_lshlrev_b32_e32 v254, 16, v225
	v_lshlrev_b32_e32 v236, 16, v35
	v_fmac_f32_e32 v252, v230, v254
	v_fmac_f32_e32 v253, v40, v236
	v_and_b32_e32 v71, 0xffff0000, v225
	v_and_b32_e32 v237, 0xffff0000, v35
	v_fmac_f32_e32 v252, v231, v71
	v_fmac_f32_e32 v253, v41, v237
	v_lshlrev_b32_e32 v254, 16, v226
	v_lshlrev_b32_e32 v236, 16, v36
	v_fmac_f32_e32 v252, v232, v254
	v_fmac_f32_e32 v253, v42, v236
	v_and_b32_e32 v71, 0xffff0000, v226
	v_and_b32_e32 v237, 0xffff0000, v36
	v_fmac_f32_e32 v252, v233, v71
	v_fmac_f32_e32 v253, v43, v237
	v_lshlrev_b32_e32 v254, 16, v227
	v_lshlrev_b32_e32 v236, 16, v37
	v_fmac_f32_e32 v252, v234, v254
	v_fmac_f32_e32 v253, v44, v236
	v_and_b32_e32 v71, 0xffff0000, v227
	v_and_b32_e32 v237, 0xffff0000, v37
	v_fmac_f32_e32 v252, v235, v71
	v_fmac_f32_e32 v253, v45, v237
	v_add_f32_e32 v242, v242, v252
	v_add_f32_e32 v242, v242, v253
	s_waitcnt lgkmcnt(0)
	v_and_b32_e32 v254, 0xffff0000, v46
	v_and_b32_e32 v236, 0xffff0000, v58
	v_mul_f32_e32 v252, v51, v254
	v_mul_f32_e32 v253, v63, v236
	v_lshlrev_b32_e32 v71, 16, v46
	v_lshlrev_b32_e32 v237, 16, v58
	v_fmac_f32_e32 v252, v50, v71
	v_fmac_f32_e32 v253, v62, v237
	v_lshlrev_b32_e32 v254, 16, v47
	v_lshlrev_b32_e32 v236, 16, v59
	v_fmac_f32_e32 v252, v52, v254
	v_fmac_f32_e32 v253, v64, v236
	v_and_b32_e32 v71, 0xffff0000, v47
	v_and_b32_e32 v237, 0xffff0000, v59
	v_fmac_f32_e32 v252, v53, v71
	v_fmac_f32_e32 v253, v65, v237
	v_lshlrev_b32_e32 v254, 16, v48
	v_lshlrev_b32_e32 v236, 16, v60
	v_fmac_f32_e32 v252, v54, v254
	v_fmac_f32_e32 v253, v208, v236
	v_and_b32_e32 v71, 0xffff0000, v48
	v_and_b32_e32 v237, 0xffff0000, v60
	v_fmac_f32_e32 v252, v55, v71
	v_fmac_f32_e32 v253, v209, v237
	v_lshlrev_b32_e32 v254, 16, v49
	v_lshlrev_b32_e32 v236, 16, v61
	v_fmac_f32_e32 v252, v56, v254
	v_fmac_f32_e32 v253, v210, v236
	v_and_b32_e32 v71, 0xffff0000, v49
	v_and_b32_e32 v237, 0xffff0000, v61
	v_fmac_f32_e32 v252, v57, v71
	v_fmac_f32_e32 v253, v211, v237
	v_add_f32_e32 v242, v242, v252
	v_mov_b32_e32 v46, v242
	v_mov_b32_e32 v34, v253
	v_exp_f32_e32 v35, v69
	v_add_f32_e32 v37, v68, v66
	v_exp_f32_e32 v36, v70
	v_mul_f32_e32 v37, 0xbfb8aa3b, v37
	v_exp_f32_e32 v37, v37
	v_add_f32_e32 v34, v46, v34
	v_mul_f32_e32 v34, v35, v34
	v_fmac_f32_e32 v34, v67, v36
	v_max_f32_e64 v34, |v34|, v37
	v_rcp_f32_e32 v34, v34
	v_cvt_pk_bf16_f32 v37, v94, v95
	v_mul_f32_e32 v35, v35, v34
	v_mul_f32_e32 v34, v36, v34
	ds_write2st64_b32 v128, v35, v34 offset0:145 offset1:146
	ds_read2_b64 v[38:41], v127 offset1:4
	ds_read2_b64 v[42:45], v136 offset0:32 offset1:36
	ds_read2_b64 v[46:49], v135 offset0:64 offset1:68
	ds_read2_b64 v[50:53], v137 offset0:96 offset1:100
	ds_read2_b64 v[54:57], v127 offset0:8 offset1:12
	ds_read2_b64 v[208:211], v136 offset0:40 offset1:44
	ds_read2_b64 v[212:215], v135 offset0:72 offset1:76
	ds_read2_b64 v[216:219], v137 offset0:104 offset1:108
	v_cvt_pk_bf16_f32 v34, v96, v97
	v_cvt_pk_bf16_f32 v35, v98, v99
	v_cvt_pk_bf16_f32 v36, v92, v93
	s_waitcnt lgkmcnt(7)
	s_nop 0
	v_mfma_f32_16x16x32_bf16 v[38:41], v[38:41], v[34:37], 0
	s_waitcnt lgkmcnt(6)
	v_mfma_f32_16x16x32_bf16 v[42:45], v[42:45], v[34:37], 0
	s_waitcnt lgkmcnt(5)
	v_mfma_f32_16x16x32_bf16 v[46:49], v[46:49], v[34:37], 0
	s_waitcnt lgkmcnt(4)
	v_mfma_f32_16x16x32_bf16 v[34:37], v[50:53], v[34:37], 0
	v_cvt_pk_bf16_f32 v50, v88, v89
	v_cvt_pk_bf16_f32 v51, v90, v91
	v_cvt_pk_bf16_f32 v52, v84, v85
	v_cvt_pk_bf16_f32 v53, v86, v87
	s_waitcnt lgkmcnt(3)
	s_nop 0
	v_mfma_f32_16x16x32_bf16 v[74:77], v[54:57], v[50:53], v[38:41]
	s_nop 2
	s_waitcnt lgkmcnt(2)
	v_mfma_f32_16x16x32_bf16 v[66:69], v[208:211], v[50:53], v[42:45]
	s_waitcnt lgkmcnt(1)
	v_mfma_f32_16x16x32_bf16 v[58:61], v[212:215], v[50:53], v[46:49]
	s_waitcnt lgkmcnt(0)
	v_mfma_f32_16x16x32_bf16 v[34:37], v[216:219], v[50:53], v[34:37]
	ds_read_b128 v[38:41], v102 offset:27648
	ds_read_b128 v[42:45], v100 offset:9216
	ds_read_b128 v[46:49], v100 offset:11520
	ds_read_b128 v[50:53], v100 offset:13824
	ds_read_b128 v[54:57], v100 offset:16128
	ds_read_b128 v[140:143], v102 offset:27712
	ds_read_b128 v[62:65], v100 offset:9280
	ds_read_b128 v[70:73], v100 offset:11584
	ds_read_b128 v[164:167], v100 offset:13888
	ds_read_b128 v[168:171], v100 offset:16192
	s_waitcnt lgkmcnt(8)
	v_mfma_f32_16x16x32_bf16 v[42:45], v[42:45], v[38:41], 0
	s_waitcnt lgkmcnt(7)
	v_mfma_f32_16x16x32_bf16 v[46:49], v[46:49], v[38:41], 0
	s_waitcnt lgkmcnt(6)
	v_mfma_f32_16x16x32_bf16 v[50:53], v[50:53], v[38:41], 0
	s_waitcnt lgkmcnt(3)
	v_mfma_f32_16x16x32_bf16 v[172:175], v[62:65], v[140:143], v[42:45]
	s_waitcnt lgkmcnt(2)
	v_mfma_f32_16x16x32_bf16 v[70:73], v[70:73], v[140:143], v[46:49]
	s_waitcnt lgkmcnt(1)
	v_mfma_f32_16x16x32_bf16 v[62:65], v[164:167], v[140:143], v[50:53]
	ds_read_b128 v[42:45], v100 offset:18432
	ds_read_b128 v[46:49], v100 offset:20736
	s_nop 0
	ds_read_b128 v[50:53], v100 offset:23040
	ds_read_b128 v[164:167], v100 offset:25344
	v_mfma_f32_16x16x32_bf16 v[54:57], v[54:57], v[38:41], 0
	s_waitcnt lgkmcnt(4)
	v_mfma_f32_16x16x32_bf16 v[54:57], v[168:171], v[140:143], v[54:57]
	s_waitcnt lgkmcnt(3)
	v_mfma_f32_16x16x32_bf16 v[42:45], v[42:45], v[38:41], 0
	s_waitcnt lgkmcnt(2)
	v_mfma_f32_16x16x32_bf16 v[46:49], v[46:49], v[38:41], 0
	s_waitcnt lgkmcnt(1)
	v_mfma_f32_16x16x32_bf16 v[168:171], v[50:53], v[38:41], 0
	s_waitcnt lgkmcnt(0)
	v_mfma_f32_16x16x32_bf16 v[38:41], v[164:167], v[38:41], 0
	ds_read_b128 v[50:53], v100 offset:18496
	ds_read_b128 v[164:167], v100 offset:20800
	ds_read_b128 v[176:179], v100 offset:23104
	ds_read_b128 v[180:183], v100 offset:25408
	s_waitcnt lgkmcnt(3)
	v_mfma_f32_16x16x32_bf16 v[50:53], v[50:53], v[140:143], v[42:45]
	s_waitcnt lgkmcnt(2)
	v_mfma_f32_16x16x32_bf16 v[46:49], v[164:167], v[140:143], v[46:49]
	s_waitcnt lgkmcnt(1)
	v_mfma_f32_16x16x32_bf16 v[42:45], v[176:179], v[140:143], v[168:171]
	v_add_u32_e32 v176, s0, v106
	s_waitcnt lgkmcnt(0)
	v_mfma_f32_16x16x32_bf16 v[38:41], v[180:183], v[140:143], v[38:41]
	ds_read_b128 v[140:143], v103 offset:37120
	ds_read_b128 v[164:167], v103 offset:37376
	v_lshl_add_u64 v[168:169], v[108:109], 0, s[0:1]
	v_add_co_u32_e32 v170, vcc, s87, v168
	s_waitcnt lgkmcnt(0)
	v_mul_f32_e32 v164, v172, v164
	v_fmac_f32_e32 v164, v74, v140
	v_cvt_pk_bf16_f32 v74, v164, s0
	v_addc_co_u32_e32 v171, vcc, 0, v169, vcc
	global_store_short v[170:171], v74, off offset:2560
	v_mul_f32_e32 v74, v173, v165
	v_fmac_f32_e32 v74, v75, v141
	v_cvt_pk_bf16_f32 v140, v74, s0
	v_add_co_u32_e32 v74, vcc, s29, v168
	v_or_b32_e32 v164, 0x20000, v176
	s_nop 0
	v_addc_co_u32_e32 v75, vcc, 0, v169, vcc
	global_store_short v[74:75], v140, off offset:2560
	v_mul_f32_e32 v74, v174, v166
	v_fmac_f32_e32 v74, v76, v142
	v_cvt_pk_bf16_f32 v76, v74, s0
	v_add_co_u32_e32 v74, vcc, s33, v168
	v_mov_b32_e32 v165, v1
	s_nop 0
	v_addc_co_u32_e32 v75, vcc, 0, v169, vcc
	global_store_short v[74:75], v76, off offset:2560
	v_mul_f32_e32 v74, v175, v167
	v_fmac_f32_e32 v74, v77, v143
	v_cvt_pk_bf16_f32 v76, v74, s0
	v_add_co_u32_e32 v74, vcc, s88, v168
	v_lshl_add_u64 v[164:165], v[104:105], 0, v[164:165]
	s_nop 0
	v_addc_co_u32_e32 v75, vcc, 0, v169, vcc
	global_store_short v[74:75], v76, off offset:2560
	ds_read_b128 v[74:77], v103 offset:37184
	ds_read_b128 v[140:143], v103 offset:37440
	s_waitcnt lgkmcnt(0)
	v_mul_f32_e32 v70, v70, v140
	v_fmac_f32_e32 v70, v66, v74
	v_cvt_pk_bf16_f32 v66, v70, s0
	global_store_short v[164:165], v66, off offset:2560
	v_mul_f32_e32 v66, v71, v141
	v_fmac_f32_e32 v66, v67, v75
	v_cvt_pk_bf16_f32 v70, v66, s0
	v_add_co_u32_e32 v66, vcc, s94, v164
	v_or_b32_e32 v74, 0x40000, v176
	s_nop 0
	v_addc_co_u32_e32 v67, vcc, 0, v165, vcc
	global_store_short v[66:67], v70, off offset:2560
	v_mul_f32_e32 v66, v72, v142
	v_fmac_f32_e32 v66, v68, v76
	v_cvt_pk_bf16_f32 v68, v66, s0
	v_add_co_u32_e32 v66, vcc, s86, v164
	v_mov_b32_e32 v75, v1
	s_nop 0
	v_addc_co_u32_e32 v67, vcc, 0, v165, vcc
	global_store_short v[66:67], v68, off offset:2560
	v_mul_f32_e32 v66, v73, v143
	v_fmac_f32_e32 v66, v69, v77
	v_cvt_pk_bf16_f32 v68, v66, s0
	v_add_co_u32_e32 v66, vcc, s82, v164
	v_lshl_add_u64 v[74:75], v[104:105], 0, v[74:75]
	s_nop 0
	v_addc_co_u32_e32 v67, vcc, 0, v165, vcc
	global_store_short v[66:67], v68, off offset:2560
	ds_read_b128 v[66:69], v103 offset:37248
	ds_read_b128 v[70:73], v103 offset:37504
	s_waitcnt lgkmcnt(0)
	v_mul_f32_e32 v62, v62, v70
	v_fmac_f32_e32 v62, v58, v66
	v_cvt_pk_bf16_f32 v58, v62, s0
	global_store_short v[74:75], v58, off offset:2560
	v_mul_f32_e32 v58, v63, v71
	v_fmac_f32_e32 v58, v59, v67
	v_cvt_pk_bf16_f32 v62, v58, s0
	v_add_co_u32_e32 v58, vcc, s94, v74
	v_or_b32_e32 v66, 0x60000, v176
	s_nop 0
	v_addc_co_u32_e32 v59, vcc, 0, v75, vcc
	global_store_short v[58:59], v62, off offset:2560
	v_mul_f32_e32 v58, v64, v72
	v_fmac_f32_e32 v58, v60, v68
	v_cvt_pk_bf16_f32 v60, v58, s0
	v_add_co_u32_e32 v58, vcc, s86, v74
	v_mov_b32_e32 v67, v1
	s_nop 0
	v_addc_co_u32_e32 v59, vcc, 0, v75, vcc
	global_store_short v[58:59], v60, off offset:2560
	v_mul_f32_e32 v58, v65, v73
	v_fmac_f32_e32 v58, v61, v69
	v_cvt_pk_bf16_f32 v60, v58, s0
	v_add_co_u32_e32 v58, vcc, s82, v74
	v_lshl_add_u64 v[66:67], v[104:105], 0, v[66:67]
	s_nop 0
	v_addc_co_u32_e32 v59, vcc, 0, v75, vcc
	global_store_short v[58:59], v60, off offset:2560
	ds_read_b128 v[58:61], v103 offset:37312
	ds_read_b128 v[62:65], v103 offset:37568
	s_waitcnt lgkmcnt(0)
	v_mul_f32_e32 v54, v54, v62
	v_fmac_f32_e32 v54, v34, v58
	v_cvt_pk_bf16_f32 v34, v54, s0
	global_store_short v[66:67], v34, off offset:2560
	v_mul_f32_e32 v34, v55, v63
	v_fmac_f32_e32 v34, v35, v59
	v_cvt_pk_bf16_f32 v54, v34, s0
	v_add_co_u32_e32 v34, vcc, s94, v66
	s_nop 1
	v_addc_co_u32_e32 v35, vcc, 0, v67, vcc
	global_store_short v[34:35], v54, off offset:2560
	v_mul_f32_e32 v34, v56, v64
	v_fmac_f32_e32 v34, v36, v60
	v_cvt_pk_bf16_f32 v36, v34, s0
	v_add_co_u32_e32 v34, vcc, s86, v66
	s_nop 1
	v_addc_co_u32_e32 v35, vcc, 0, v67, vcc
	global_store_short v[34:35], v36, off offset:2560
	v_mul_f32_e32 v34, v57, v65
	v_fmac_f32_e32 v34, v37, v61
	v_cvt_pk_bf16_f32 v36, v34, s0
	v_add_co_u32_e32 v34, vcc, s82, v66
	s_add_u32 s0, s0, 0x80000
	s_nop 0
	v_addc_co_u32_e32 v35, vcc, 0, v67, vcc
	global_store_short v[34:35], v36, off offset:2560
	v_max_f32_e32 v34, v120, v120
	v_max_f32_e32 v35, v139, v34
	v_sub_f32_e32 v36, v120, v35
	v_sub_f32_e32 v34, v83, v35
	v_mul_f32_e32 v36, 0x3fb8aa3b, v36
	v_mul_f32_e32 v34, 0x3fb8aa3b, v34
	v_exp_f32_e32 v36, v36
	v_exp_f32_e32 v34, v34
	s_addc_u32 s1, s1, 0
	s_add_u32 s42, s42, 0x500
	v_pk_mul_f32 v[52:53], v[36:37], v[52:53] op_sel_hi:[0,1]
	v_pk_mul_f32 v[50:51], v[36:37], v[50:51] op_sel_hi:[0,1]
	v_pk_mul_f32 v[48:49], v[36:37], v[48:49] op_sel_hi:[0,1]
	v_pk_mul_f32 v[46:47], v[36:37], v[46:47] op_sel_hi:[0,1]
	v_pk_mul_f32 v[44:45], v[36:37], v[44:45] op_sel_hi:[0,1]
	v_pk_mul_f32 v[42:43], v[36:37], v[42:43] op_sel_hi:[0,1]
	v_pk_mul_f32 v[40:41], v[36:37], v[40:41] op_sel_hi:[0,1]
	v_pk_mul_f32 v[38:39], v[36:37], v[38:39] op_sel_hi:[0,1]
	v_pk_fma_f32 v[98:99], v[98:99], v[34:35], v[52:53] op_sel_hi:[1,0,1]
	v_pk_fma_f32 v[96:97], v[96:97], v[34:35], v[50:51] op_sel_hi:[1,0,1]
	v_pk_fma_f32 v[94:95], v[94:95], v[34:35], v[48:49] op_sel_hi:[1,0,1]
	v_pk_fma_f32 v[92:93], v[92:93], v[34:35], v[46:47] op_sel_hi:[1,0,1]
	v_pk_fma_f32 v[90:91], v[90:91], v[34:35], v[44:45] op_sel_hi:[1,0,1]
	v_pk_fma_f32 v[88:89], v[88:89], v[34:35], v[42:43] op_sel_hi:[1,0,1]
	v_pk_fma_f32 v[86:87], v[86:87], v[34:35], v[40:41] op_sel_hi:[1,0,1]
	v_pk_fma_f32 v[84:85], v[84:85], v[34:35], v[38:39] op_sel_hi:[1,0,1]
	v_mul_f32_e32 v120, v82, v34
	v_mul_f32_e32 v34, v138, v36
	s_addc_u32 s43, s43, 0
	v_pk_add_f32 v[82:83], v[120:121], v[34:35]
	s_cmp_eq_u32 s0, 0xf80000
	s_barrier
	s_cbranch_scc0 .LBB0_465
	s_waitcnt vmcnt(20)
	v_max_f32_e32 v0, v134, v134
	v_max_f32_e32 v44, v83, v83
	v_max_f32_e32 v0, v44, v0
	ds_write_b128 v133, v[2:5]
	ds_write_b128 v133, v[6:9] offset:9216
	ds_write_b128 v133, v[10:13] offset:18432
	ds_write_b128 v133, v[14:17] offset:27648
	ds_write_b128 v132, v[18:21]
	ds_write_b128 v132, v[22:25] offset:9216
	ds_write_b128 v132, v[26:29] offset:18432
	ds_write_b128 v132, v[30:33] offset:27648
	v_sub_f32_e32 v2, v83, v0
	s_waitcnt lgkmcnt(0)
	s_barrier
	ds_write_b32 v128, v82 offset:36864
	v_mul_f32_e32 v34, 0x3fb8aa3b, v2
	s_waitcnt vmcnt(17)
	v_sub_f32_e32 v2, v125, v0
	v_mul_f32_e32 v35, 0x3fb8aa3b, v2
	ds_read_b128 v[2:5], v129 offset:36864
	ds_read_b128 v[6:9], v129 offset:36880
	ds_read_b128 v[10:13], v129 offset:36896
	ds_read_b128 v[14:17], v107
	ds_read_b128 v[18:21], v129 offset:36912
	ds_read_b128 v[22:25], v107 offset:16
	ds_read_b128 v[26:29], v107 offset:32
	ds_read_b128 v[30:33], v107 offset:48
	s_waitcnt lgkmcnt(4)
	v_lshlrev_b32_e32 v36, 16, v14
	v_and_b32_e32 v14, 0xffff0000, v14
	v_mul_f32_e32 v3, v3, v14
	v_fmac_f32_e32 v3, v2, v36
	v_lshlrev_b32_e32 v2, 16, v15
	v_fmac_f32_e32 v3, v4, v2
	v_and_b32_e32 v2, 0xffff0000, v15
	v_fmac_f32_e32 v3, v5, v2
	v_lshlrev_b32_e32 v2, 16, v16
	v_fmac_f32_e32 v3, v6, v2
	v_and_b32_e32 v2, 0xffff0000, v16
	v_fmac_f32_e32 v3, v7, v2
	v_lshlrev_b32_e32 v2, 16, v17
	v_fmac_f32_e32 v3, v8, v2
	v_and_b32_e32 v2, 0xffff0000, v17
	v_fmac_f32_e32 v3, v9, v2
	v_add_f32_e32 v6, 0, v3
	s_waitcnt lgkmcnt(2)
	v_and_b32_e32 v3, 0xffff0000, v22
	v_lshlrev_b32_e32 v2, 16, v22
	v_mul_f32_e32 v7, v11, v3
	v_fmac_f32_e32 v7, v10, v2
	v_lshlrev_b32_e32 v2, 16, v23
	v_fmac_f32_e32 v7, v12, v2
	v_and_b32_e32 v2, 0xffff0000, v23
	v_fmac_f32_e32 v7, v13, v2
	v_lshlrev_b32_e32 v2, 16, v24
	v_fmac_f32_e32 v7, v18, v2
	v_and_b32_e32 v2, 0xffff0000, v24
	v_fmac_f32_e32 v7, v19, v2
	v_lshlrev_b32_e32 v2, 16, v25
	v_fmac_f32_e32 v7, v20, v2
	v_and_b32_e32 v2, 0xffff0000, v25
	v_fmac_f32_e32 v7, v21, v2
	ds_read_b128 v[2:5], v129 offset:36928
	v_add_f32_e32 v10, v6, v7
	ds_read_b128 v[6:9], v129 offset:36944
	s_waitcnt lgkmcnt(3)
	v_and_b32_e32 v12, 0xffff0000, v26
	v_lshlrev_b32_e32 v11, 16, v26
	s_waitcnt lgkmcnt(1)
	v_mul_f32_e32 v12, v3, v12
	v_fmac_f32_e32 v12, v2, v11
	v_lshlrev_b32_e32 v2, 16, v27
	v_fmac_f32_e32 v12, v4, v2
	v_and_b32_e32 v2, 0xffff0000, v27
	v_fmac_f32_e32 v12, v5, v2
	v_lshlrev_b32_e32 v2, 16, v28
	s_waitcnt lgkmcnt(0)
	v_fmac_f32_e32 v12, v6, v2
	v_and_b32_e32 v2, 0xffff0000, v28
	v_fmac_f32_e32 v12, v7, v2
	v_lshlrev_b32_e32 v2, 16, v29
	v_fmac_f32_e32 v12, v8, v2
	v_and_b32_e32 v2, 0xffff0000, v29
	v_fmac_f32_e32 v12, v9, v2
	ds_read_b128 v[2:5], v129 offset:36960
	ds_read_b128 v[6:9], v129 offset:36976
	v_add_f32_e32 v10, v10, v12
	v_and_b32_e32 v12, 0xffff0000, v30
	v_lshlrev_b32_e32 v11, 16, v30
	s_waitcnt lgkmcnt(1)
	v_mul_f32_e32 v12, v3, v12
	v_fmac_f32_e32 v12, v2, v11
	v_lshlrev_b32_e32 v2, 16, v31
	v_fmac_f32_e32 v12, v4, v2
	v_and_b32_e32 v2, 0xffff0000, v31
	v_fmac_f32_e32 v12, v5, v2
	v_lshlrev_b32_e32 v2, 16, v32
	s_waitcnt lgkmcnt(0)
	v_fmac_f32_e32 v12, v6, v2
	v_and_b32_e32 v2, 0xffff0000, v32
	v_fmac_f32_e32 v12, v7, v2
	v_lshlrev_b32_e32 v2, 16, v33
	v_fmac_f32_e32 v12, v8, v2
	v_and_b32_e32 v6, 0xffff0000, v33
	ds_read_b128 v[2:5], v107 offset:64
	v_fmac_f32_e32 v12, v9, v6
	ds_read_b128 v[6:9], v129 offset:36992
	v_add_f32_e32 v14, v10, v12
	ds_read_b128 v[10:13], v129 offset:37008
	s_waitcnt lgkmcnt(2)
	v_lshlrev_b32_e32 v15, 16, v2
	v_and_b32_e32 v2, 0xffff0000, v2
	s_waitcnt lgkmcnt(1)
	v_mul_f32_e32 v16, v7, v2
	v_fmac_f32_e32 v16, v6, v15
	v_lshlrev_b32_e32 v2, 16, v3
	v_fmac_f32_e32 v16, v8, v2
	v_and_b32_e32 v2, 0xffff0000, v3
	v_fmac_f32_e32 v16, v9, v2
	v_lshlrev_b32_e32 v2, 16, v4
	s_waitcnt lgkmcnt(0)
	v_fmac_f32_e32 v16, v10, v2
	v_and_b32_e32 v2, 0xffff0000, v4
	v_fmac_f32_e32 v16, v11, v2
	v_lshlrev_b32_e32 v2, 16, v5
	v_fmac_f32_e32 v16, v12, v2
	v_and_b32_e32 v6, 0xffff0000, v5
	ds_read_b128 v[2:5], v107 offset:80
	v_fmac_f32_e32 v16, v13, v6
	ds_read_b128 v[6:9], v129 offset:37024
	ds_read_b128 v[10:13], v129 offset:37040
	v_add_f32_e32 v14, v14, v16
	s_waitcnt lgkmcnt(2)
	v_lshlrev_b32_e32 v15, 16, v2
	v_and_b32_e32 v2, 0xffff0000, v2
	s_waitcnt lgkmcnt(1)
	v_mul_f32_e32 v16, v7, v2
	v_fmac_f32_e32 v16, v6, v15
	v_lshlrev_b32_e32 v2, 16, v3
	v_fmac_f32_e32 v16, v8, v2
	v_and_b32_e32 v2, 0xffff0000, v3
	v_fmac_f32_e32 v16, v9, v2
	v_lshlrev_b32_e32 v2, 16, v4
	s_waitcnt lgkmcnt(0)
	v_fmac_f32_e32 v16, v10, v2
	v_and_b32_e32 v2, 0xffff0000, v4
	v_fmac_f32_e32 v16, v11, v2
	v_lshlrev_b32_e32 v2, 16, v5
	v_fmac_f32_e32 v16, v12, v2
	v_and_b32_e32 v6, 0xffff0000, v5
	ds_read_b128 v[2:5], v107 offset:96
	v_fmac_f32_e32 v16, v13, v6
	ds_read_b128 v[6:9], v129 offset:37056
	ds_read_b128 v[10:13], v129 offset:37072
	v_add_f32_e32 v14, v14, v16
	s_waitcnt lgkmcnt(2)
	v_lshlrev_b32_e32 v15, 16, v2
	v_and_b32_e32 v2, 0xffff0000, v2
	s_waitcnt lgkmcnt(1)
	v_mul_f32_e32 v16, v7, v2
	v_fmac_f32_e32 v16, v6, v15
	v_lshlrev_b32_e32 v2, 16, v3
	v_fmac_f32_e32 v16, v8, v2
	v_and_b32_e32 v2, 0xffff0000, v3
	v_fmac_f32_e32 v16, v9, v2
	v_lshlrev_b32_e32 v2, 16, v4
	s_waitcnt lgkmcnt(0)
	v_fmac_f32_e32 v16, v10, v2
	v_and_b32_e32 v2, 0xffff0000, v4
	v_fmac_f32_e32 v16, v11, v2
	v_lshlrev_b32_e32 v2, 16, v5
	v_fmac_f32_e32 v16, v12, v2
	v_and_b32_e32 v6, 0xffff0000, v5
	ds_read_b128 v[2:5], v107 offset:112
	v_fmac_f32_e32 v16, v13, v6
	ds_read_b128 v[6:9], v129 offset:37088
	ds_read_b128 v[10:13], v129 offset:37104
	v_add_f32_e32 v0, v131, v0
	s_waitcnt lgkmcnt(2)
	v_lshlrev_b32_e32 v15, 16, v2
	v_and_b32_e32 v2, 0xffff0000, v2
	s_waitcnt lgkmcnt(1)
	v_mul_f32_e32 v2, v7, v2
	v_fmac_f32_e32 v2, v6, v15
	v_lshlrev_b32_e32 v6, 16, v3
	v_fmac_f32_e32 v2, v8, v6
	v_and_b32_e32 v3, 0xffff0000, v3
	v_fmac_f32_e32 v2, v9, v3
	v_lshlrev_b32_e32 v3, 16, v4
	s_waitcnt lgkmcnt(0)
	v_fmac_f32_e32 v2, v10, v3
	v_and_b32_e32 v3, 0xffff0000, v4
	v_fmac_f32_e32 v2, v11, v3
	v_lshlrev_b32_e32 v3, 16, v5
	v_fmac_f32_e32 v2, v12, v3
	v_and_b32_e32 v3, 0xffff0000, v5
	v_fmac_f32_e32 v2, v13, v3
	v_exp_f32_e32 v3, v34
	v_exp_f32_e32 v4, v35
	v_mul_f32_e32 v0, 0xbfb8aa3b, v0
	v_add_f32_e32 v14, v14, v16
	v_exp_f32_e32 v0, v0
	v_add_f32_e32 v2, v14, v2
	v_mul_f32_e32 v2, v3, v2
	v_fmac_f32_e32 v2, v130, v4
	v_max_f32_e64 v0, |v2|, v0
	v_rcp_f32_e32 v0, v0
	v_cvt_pk_bf16_f32 v10, v96, v97
	v_cvt_pk_bf16_f32 v11, v98, v99
	v_cvt_pk_bf16_f32 v12, v92, v93
	v_mul_f32_e32 v2, v3, v0
	v_mul_f32_e32 v0, v4, v0
	ds_write2st64_b32 v128, v2, v0 offset0:145 offset1:146
	ds_read2_b64 v[2:5], v127 offset1:4
	ds_read2_b64 v[6:9], v136 offset0:32 offset1:36
	ds_read2_b64 v[14:17], v135 offset0:64 offset1:68
	ds_read2_b64 v[18:21], v137 offset0:96 offset1:100
	ds_read2_b64 v[22:25], v127 offset0:8 offset1:12
	v_cvt_pk_bf16_f32 v13, v94, v95
	v_cvt_pk_bf16_f32 v34, v88, v89
	v_cvt_pk_bf16_f32 v35, v90, v91
	s_waitcnt lgkmcnt(4)
	v_mfma_f32_16x16x32_bf16 v[2:5], v[2:5], v[10:13], 0
	v_cvt_pk_bf16_f32 v36, v84, v85
	v_cvt_pk_bf16_f32 v37, v86, v87
	v_or_b32_e32 v0, s39, v126
	s_waitcnt lgkmcnt(3)
	v_mfma_f32_16x16x32_bf16 v[6:9], v[6:9], v[10:13], 0
	v_lshlrev_b32_e32 v0, 13, v0
	v_lshl_add_u64 v[42:43], s[30:31], 0, v[0:1]
	v_lshl_add_u64 v[42:43], v[42:43], 0, s[2:3]
	s_waitcnt lgkmcnt(2)
	v_mfma_f32_16x16x32_bf16 v[14:17], v[14:17], v[10:13], 0
	v_lshl_add_u64 v[42:43], v[80:81], 1, v[42:43]
	v_readlane_b32 s2, v239, 11
	v_readlane_b32 s4, v239, 12
	s_waitcnt lgkmcnt(1)
	v_mfma_f32_16x16x32_bf16 v[10:13], v[18:21], v[10:13], 0
	ds_read2_b64 v[18:21], v136 offset0:40 offset1:44
	s_waitcnt lgkmcnt(1)
	v_mfma_f32_16x16x32_bf16 v[46:49], v[22:25], v[34:37], v[2:5]
	s_nop 2
	ds_read2_b64 v[2:5], v135 offset0:72 offset1:76
	s_waitcnt lgkmcnt(1)
	v_mfma_f32_16x16x32_bf16 v[30:33], v[18:21], v[34:37], v[6:9]
	ds_read_b128 v[18:21], v100 offset:13824
	s_nop 1
	ds_read2_b64 v[6:9], v137 offset0:104 offset1:108
	s_waitcnt lgkmcnt(2)
	v_mfma_f32_16x16x32_bf16 v[26:29], v[2:5], v[34:37], v[14:17]
	s_nop 2
	ds_read_b128 v[14:17], v100 offset:9216
	s_waitcnt lgkmcnt(1)
	v_mfma_f32_16x16x32_bf16 v[2:5], v[6:9], v[34:37], v[10:13]
	s_nop 2
	ds_read_b128 v[10:13], v102 offset:27648
	s_waitcnt lgkmcnt(0)
	v_mfma_f32_16x16x32_bf16 v[6:9], v[14:17], v[10:13], 0
	ds_read_b128 v[14:17], v100 offset:11520
	ds_read_b128 v[22:25], v100 offset:16128
	ds_read_b128 v[34:37], v100 offset:9280
	ds_read_b128 v[50:53], v102 offset:27712
	ds_read_b128 v[38:41], v100 offset:11584
	s_waitcnt lgkmcnt(4)
	v_mfma_f32_16x16x32_bf16 v[14:17], v[14:17], v[10:13], 0
	ds_read_b128 v[58:61], v100 offset:25344
	ds_read_b128 v[62:65], v100 offset:18496
	ds_read_b128 v[66:69], v100 offset:20800
	s_waitcnt lgkmcnt(4)
	v_mfma_f32_16x16x32_bf16 v[54:57], v[34:37], v[50:53], v[6:9]
	s_nop 2
	ds_read_b128 v[6:9], v100 offset:13888
	s_waitcnt lgkmcnt(4)
	v_mfma_f32_16x16x32_bf16 v[38:41], v[38:41], v[50:53], v[14:17]
	s_nop 2
	ds_read_b128 v[14:17], v100 offset:16192
	v_mfma_f32_16x16x32_bf16 v[18:21], v[18:21], v[10:13], 0
	v_mfma_f32_16x16x32_bf16 v[22:25], v[22:25], v[10:13], 0
	s_waitcnt lgkmcnt(1)
	v_mfma_f32_16x16x32_bf16 v[34:37], v[6:9], v[50:53], v[18:21]
	s_nop 4
	ds_read_b128 v[18:21], v100 offset:18432
	s_waitcnt lgkmcnt(1)
	v_mfma_f32_16x16x32_bf16 v[6:9], v[14:17], v[50:53], v[22:25]
	ds_read_b128 v[14:17], v100 offset:20736
	s_nop 1
	ds_read_b128 v[22:25], v100 offset:23040
	s_waitcnt lgkmcnt(2)
	v_mfma_f32_16x16x32_bf16 v[18:21], v[18:21], v[10:13], 0
	s_waitcnt lgkmcnt(1)
	v_mfma_f32_16x16x32_bf16 v[14:17], v[14:17], v[10:13], 0
	s_waitcnt lgkmcnt(0)
	v_mfma_f32_16x16x32_bf16 v[22:25], v[22:25], v[10:13], 0
	v_mfma_f32_16x16x32_bf16 v[58:61], v[58:61], v[10:13], 0
	v_mfma_f32_16x16x32_bf16 v[10:13], v[62:65], v[50:53], v[18:21]
	ds_read_b128 v[62:65], v100 offset:25408
	s_nop 1
	ds_read_b128 v[18:21], v100 offset:23104
	v_mfma_f32_16x16x32_bf16 v[14:17], v[66:69], v[50:53], v[14:17]
	ds_read_b128 v[66:69], v103 offset:37376
	ds_read_b128 v[70:73], v103 offset:37120
	s_waitcnt lgkmcnt(1)
	v_mul_f32_e32 v0, v54, v66
	s_waitcnt lgkmcnt(0)
	v_fmac_f32_e32 v0, v46, v70
	v_cvt_pk_bf16_f32 v0, v0, s0
	s_mov_b32 s0, 0xf80000
	v_mfma_f32_16x16x32_bf16 v[18:21], v[18:21], v[50:53], v[22:25]
	v_mfma_f32_16x16x32_bf16 v[22:25], v[62:65], v[50:53], v[58:61]
	v_add_co_u32_e32 v50, vcc, s0, v42
	s_nop 1
	v_addc_co_u32_e32 v51, vcc, 0, v43, vcc
	global_store_short v[50:51], v0, off offset:2560
	v_mul_f32_e32 v0, v55, v67
	v_fmac_f32_e32 v0, v47, v71
	v_cvt_pk_bf16_f32 v0, v0, s0
	s_mov_b32 s0, 0xf82000
	v_add_co_u32_e32 v46, vcc, s0, v42
	s_nop 1
	v_addc_co_u32_e32 v47, vcc, 0, v43, vcc
	global_store_short v[46:47], v0, off offset:2560
	v_mul_f32_e32 v0, v56, v68
	v_fmac_f32_e32 v0, v48, v72
	v_cvt_pk_bf16_f32 v0, v0, s0
	s_mov_b32 s0, 0xf84000
	v_add_co_u32_e32 v46, vcc, s0, v42
	s_nop 1
	v_addc_co_u32_e32 v47, vcc, 0, v43, vcc
	global_store_short v[46:47], v0, off offset:2560
	v_mul_f32_e32 v0, v57, v69
	v_fmac_f32_e32 v0, v49, v73
	ds_read_b128 v[46:49], v103 offset:37440
	ds_read_b128 v[50:53], v103 offset:37184
	v_cvt_pk_bf16_f32 v0, v0, s0
	s_mov_b32 s0, 0xf86000
	v_add_co_u32_e32 v54, vcc, s0, v42
	s_nop 1
	v_addc_co_u32_e32 v55, vcc, 0, v43, vcc
	global_store_short v[54:55], v0, off offset:2560
	s_waitcnt lgkmcnt(1)
	v_mul_f32_e32 v0, v38, v46
	s_waitcnt lgkmcnt(0)
	v_fmac_f32_e32 v0, v30, v50
	v_cvt_pk_bf16_f32 v0, v0, s0
	s_mov_b32 s0, 0xfa0000
	v_add_co_u32_e32 v54, vcc, s0, v42
	s_nop 1
	v_addc_co_u32_e32 v55, vcc, 0, v43, vcc
	global_store_short v[54:55], v0, off offset:2560
	v_mul_f32_e32 v0, v39, v47
	v_fmac_f32_e32 v0, v31, v51
	v_cvt_pk_bf16_f32 v0, v0, s0
	s_mov_b32 s0, 0xfa2000
	v_add_co_u32_e32 v30, vcc, s0, v42
	s_nop 1
	v_addc_co_u32_e32 v31, vcc, 0, v43, vcc
	global_store_short v[30:31], v0, off offset:2560
	v_mul_f32_e32 v0, v40, v48
	v_fmac_f32_e32 v0, v32, v52
	v_cvt_pk_bf16_f32 v0, v0, s0
	s_mov_b32 s0, 0xfa4000
	v_add_co_u32_e32 v30, vcc, s0, v42
	s_nop 1
	v_addc_co_u32_e32 v31, vcc, 0, v43, vcc
	global_store_short v[30:31], v0, off offset:2560
	v_mul_f32_e32 v0, v41, v49
	v_fmac_f32_e32 v0, v33, v53
	ds_read_b128 v[30:33], v103 offset:37504
	ds_read_b128 v[38:41], v103 offset:37248
	v_cvt_pk_bf16_f32 v0, v0, s0
	s_mov_b32 s0, 0xfa6000
	v_add_co_u32_e32 v46, vcc, s0, v42
	s_nop 1
	v_addc_co_u32_e32 v47, vcc, 0, v43, vcc
	global_store_short v[46:47], v0, off offset:2560
	s_waitcnt lgkmcnt(1)
	v_mul_f32_e32 v0, v34, v30
	s_waitcnt lgkmcnt(0)
	v_fmac_f32_e32 v0, v26, v38
	v_cvt_pk_bf16_f32 v0, v0, s0
	s_mov_b32 s0, 0xfc0000
	v_add_co_u32_e32 v46, vcc, s0, v42
	s_nop 1
	v_addc_co_u32_e32 v47, vcc, 0, v43, vcc
	global_store_short v[46:47], v0, off offset:2560
	v_mul_f32_e32 v0, v35, v31
	v_fmac_f32_e32 v0, v27, v39
	v_cvt_pk_bf16_f32 v0, v0, s0
	s_mov_b32 s0, 0xfc2000
	v_add_co_u32_e32 v26, vcc, s0, v42
	s_nop 1
	v_addc_co_u32_e32 v27, vcc, 0, v43, vcc
	global_store_short v[26:27], v0, off offset:2560
	v_mul_f32_e32 v0, v36, v32
	v_fmac_f32_e32 v0, v28, v40
	v_cvt_pk_bf16_f32 v0, v0, s0
	s_mov_b32 s0, 0xfc4000
	v_add_co_u32_e32 v26, vcc, s0, v42
	s_nop 1
	v_addc_co_u32_e32 v27, vcc, 0, v43, vcc
	global_store_short v[26:27], v0, off offset:2560
	v_mul_f32_e32 v0, v37, v33
	v_fmac_f32_e32 v0, v29, v41
	ds_read_b128 v[26:29], v103 offset:37568
	ds_read_b128 v[30:33], v103 offset:37312
	v_cvt_pk_bf16_f32 v0, v0, s0
	s_mov_b32 s0, 0xfc6000
	v_add_co_u32_e32 v34, vcc, s0, v42
	s_nop 1
	v_addc_co_u32_e32 v35, vcc, 0, v43, vcc
	global_store_short v[34:35], v0, off offset:2560
	s_waitcnt lgkmcnt(1)
	v_mul_f32_e32 v0, v6, v26
	s_waitcnt lgkmcnt(0)
	v_fmac_f32_e32 v0, v2, v30
	v_cvt_pk_bf16_f32 v0, v0, s0
	s_mov_b32 s0, 0xfe0000
	v_add_co_u32_e32 v34, vcc, s0, v42
	s_nop 1
	v_addc_co_u32_e32 v35, vcc, 0, v43, vcc
	global_store_short v[34:35], v0, off offset:2560
	v_mul_f32_e32 v0, v7, v27
	v_fmac_f32_e32 v0, v3, v31
	v_cvt_pk_bf16_f32 v0, v0, s0
	s_mov_b32 s0, 0xfe2000
	v_add_co_u32_e32 v2, vcc, s0, v42
	s_nop 1
	v_addc_co_u32_e32 v3, vcc, 0, v43, vcc
	global_store_short v[2:3], v0, off offset:2560
	v_mul_f32_e32 v0, v8, v28
	v_fmac_f32_e32 v0, v4, v32
	v_cvt_pk_bf16_f32 v0, v0, s0
	s_mov_b32 s0, 0xfe4000
	v_add_co_u32_e32 v2, vcc, s0, v42
	s_nop 1
	v_addc_co_u32_e32 v3, vcc, 0, v43, vcc
	global_store_short v[2:3], v0, off offset:2560
	v_mul_f32_e32 v0, v9, v29
	v_fmac_f32_e32 v0, v5, v33
	v_cvt_pk_bf16_f32 v0, v0, s0
	s_mov_b32 s0, 0xfe6000
	v_add_co_u32_e32 v6, vcc, s0, v42
	v_readlane_b32 s0, v239, 53
	v_max_f32_e32 v2, v125, v125
	s_lshl_b32 s0, s0, 3
	v_max_f32_e32 v3, v44, v2
	s_add_i32 s0, s38, s0
	v_sub_f32_e32 v2, v125, v3
	s_ashr_i32 s1, s0, 31
	v_sub_f32_e32 v4, v83, v3
	v_mul_f32_e32 v2, 0x3fb8aa3b, v2
	s_lshl_b64 s[38:39], s[0:1], 16
	v_exp_f32_e32 v2, v2
	v_mul_f32_e32 v4, 0x3fb8aa3b, v4
	s_add_u32 s2, s2, s38
	v_exp_f32_e32 v4, v4
	s_addc_u32 s39, s4, s39
	s_lshl_b32 s38, s40, 14
	s_add_u32 s38, s2, s38
	v_addc_co_u32_e32 v7, vcc, 0, v43, vcc
	s_addc_u32 s39, s39, 0
	global_store_short v[6:7], v0, off offset:2560
	v_pk_mul_f32 v[6:7], v[2:3], v[12:13] op_sel_hi:[0,1]
	v_pk_mul_f32 v[8:9], v[2:3], v[10:11] op_sel_hi:[0,1]
	v_pk_mul_f32 v[12:13], v[2:3], v[14:15] op_sel_hi:[0,1]
	v_pk_mul_f32 v[14:15], v[2:3], v[20:21] op_sel_hi:[0,1]
	v_pk_mul_f32 v[20:21], v[2:3], v[22:23] op_sel_hi:[0,1]
	v_lshl_add_u64 v[22:23], v[80:81], 2, s[38:39]
	v_lshlrev_b32_e32 v0, 10, v101
	v_pk_fma_f32 v[6:7], v[4:5], v[98:99], v[6:7] op_sel_hi:[0,1,1]
	v_pk_fma_f32 v[8:9], v[4:5], v[96:97], v[8:9] op_sel_hi:[0,1,1]
	v_lshl_add_u64 v[22:23], v[22:23], 0, v[0:1]
	s_barrier
	global_store_dword v[22:23], v8, off
	global_store_dword v[22:23], v9, off offset:256
	global_store_dword v[22:23], v6, off offset:512
	global_store_dword v[22:23], v7, off offset:768
	v_add_co_u32_e32 v6, vcc, s93, v22
	v_pk_mul_f32 v[10:11], v[2:3], v[16:17] op_sel_hi:[0,1]
	s_nop 0
	v_addc_co_u32_e32 v7, vcc, 0, v23, vcc
	v_add_co_u32_e32 v8, vcc, s94, v22
	v_pk_fma_f32 v[12:13], v[4:5], v[92:93], v[12:13] op_sel_hi:[0,1,1]
	v_pk_mul_f32 v[16:17], v[2:3], v[18:19] op_sel_hi:[0,1]
	v_addc_co_u32_e32 v9, vcc, 0, v23, vcc
	v_pk_fma_f32 v[10:11], v[4:5], v[94:95], v[10:11] op_sel_hi:[0,1,1]
	v_pk_fma_f32 v[14:15], v[4:5], v[90:91], v[14:15] op_sel_hi:[0,1,1]
	v_pk_fma_f32 v[16:17], v[4:5], v[88:89], v[16:17] op_sel_hi:[0,1,1]
	global_store_dword v[8:9], v12, off offset:-4096
	global_store_dword v[6:7], v13, off offset:256
	global_store_dword v[6:7], v10, off offset:512
	global_store_dword v[6:7], v11, off offset:768
	global_store_dword v[8:9], v16, off
	global_store_dword v[8:9], v17, off offset:256
	global_store_dword v[8:9], v14, off offset:512
	global_store_dword v[8:9], v15, off offset:768
	v_add_co_u32_e32 v6, vcc, 0x3000, v22
	v_pk_mul_f32 v[18:19], v[2:3], v[24:25] op_sel_hi:[0,1]
	s_nop 0
	v_addc_co_u32_e32 v7, vcc, 0, v23, vcc
	v_pk_fma_f32 v[20:21], v[4:5], v[84:85], v[20:21] op_sel_hi:[0,1,1]
	v_cmp_gt_u32_e32 vcc, 64, v79
	v_pk_fma_f32 v[18:19], v[4:5], v[86:87], v[18:19] op_sel_hi:[0,1,1]
	global_store_dword v[6:7], v20, off
	global_store_dword v[6:7], v21, off offset:256
	global_store_dword v[6:7], v18, off offset:512
	global_store_dword v[6:7], v19, off offset:768
	s_and_saveexec_b64 s[38:39], vcc
	s_cbranch_execz .LBB0_469
	s_lshl_b64 s[42:43], s[0:1], 10
	s_add_u32 s1, s24, s42
	s_addc_u32 s2, s25, s43
	s_lshl_b32 s41, s40, 8
	v_mov_b32_e32 v83, v119
	v_mov_b32_e32 v5, v2
	s_add_u32 s42, s1, s41
	v_pk_mul_f32 v[4:5], v[82:83], v[4:5]
	s_addc_u32 s43, s2, 0
	v_lshlrev_b32_e32 v0, 2, v78
	v_add_f32_e32 v2, v4, v5
	v_lshl_add_u64 v[4:5], s[42:43], 0, v[0:1]
	v_add_co_u32_e32 v4, vcc, 0x4950000, v4
	s_nop 1
	v_addc_co_u32_e32 v5, vcc, 0, v5, vcc
	v_cmp_eq_u32_e32 vcc, 0, v78
	global_store_dword v[4:5], v2, off
	s_and_b64 exec, exec, vcc
	s_cbranch_execz .LBB0_469
	s_mul_hi_i32 s41, s0, 0xfffffc10
	s_mulk_i32 s0, 0xfc10
	s_add_u32 s0, s1, s0
	s_addc_u32 s1, s2, s41
	s_lshl_b32 s2, s40, 2
	s_add_u32 s0, s0, s2
	s_waitcnt vmcnt(49)
	v_add_f32_e32 v0, v117, v3
	s_addc_u32 s1, s1, 0
	global_store_dword v147, v0, s[0:1]

.LBB0_673:
	s_andn2_b64 vcc, exec, s[0:1]
	s_cbranch_vccnz .LBB0_709
	v_readlane_b32 s0, v239, 54
	s_cmp_lg_u32 s0, 0
	s_cbranch_scc1 .LBB0_709
	v_and_b32_e32 v137, 63, v144
	v_lshrrev_b32_e32 v138, 6, v144
	v_lshlrev_b32_e32 v0, 10, v138
	s_nop 0
	v_readfirstlane_b32 s38, v0
	v_lshrrev_b32_e32 v139, 3, v137
	v_lshl_add_u32 v139, v138, 3, v139
	v_lshrrev_b32_e32 v140, 1, v139
	v_xor_b32_e32 v140, v140, v137
	v_and_b32_e32 v140, 7, v140
	v_lshlrev_b32_e32 v140, 4, v140
	v_add_u32_e32 v141, 0, v139
	v_lshl_add_u32 v114, v141, 11, v140
	v_add_u32_e32 v141, 32, v139
	v_lshl_add_u32 v115, v141, 11, v140
	v_add_u32_e32 v141, 64, v139
	v_lshl_add_u32 v116, v141, 11, v140
	v_add_u32_e32 v141, 96, v139
	v_lshl_add_u32 v117, v141, 11, v140
	v_add_u32_e32 v141, 128, v139
	v_lshl_add_u32 v118, v141, 11, v140
	v_and_b32_e32 v142, 15, v137
	v_lshrrev_b32_e32 v143, 4, v137
	v_lshrrev_b32_e32 v204, 1, v138
	v_and_b32_e32 v205, 1, v138
	v_bfe_u32 v208, v137, 1, 3
	v_add_u32_e32 v206, 0, v143
	v_xor_b32_e32 v206, v206, v208
	v_lshlrev_b32_e32 v206, 4, v206
	v_lshl_add_u32 v127, v142, 7, v206
	v_lshl_add_u32 v119, v204, 13, v127
	v_lshl_add_u32 v121, v205, 13, v127
	v_add_u32_e32 v121, 0x4000, v121
	v_add_u32_e32 v127, 0x8000, v127
	v_add_u32_e32 v206, 4, v143
	v_xor_b32_e32 v206, v206, v208
	v_lshlrev_b32_e32 v206, 4, v206
	v_lshl_add_u32 v128, v142, 7, v206
	v_lshl_add_u32 v120, v204, 13, v128
	v_lshl_add_u32 v126, v205, 13, v128
	v_add_u32_e32 v126, 0x4000, v126
	v_add_u32_e32 v128, 0x8000, v128
	v_lshl_add_u32 v207, v204, 6, v142
	v_lshlrev_b32_e32 v141, 3, v143
	v_lshl_add_u32 v141, v205, 7, v141
	v_add_u32_e32 v0, 0, v207
	v_lshl_add_u32 v129, v0, 13, v141
	v_lshlrev_b32_e32 v133, 6, v0
	v_lshl_add_u32 v133, v143, 4, v133
	v_add_u32_e32 v0, 16, v207
	v_lshl_add_u32 v130, v0, 13, v141
	v_lshlrev_b32_e32 v134, 6, v0
	v_lshl_add_u32 v134, v143, 4, v134
	v_add_u32_e32 v0, 32, v207
	v_lshl_add_u32 v131, v0, 13, v141
	v_lshlrev_b32_e32 v135, 6, v0
	v_lshl_add_u32 v135, v143, 4, v135
	v_add_u32_e32 v0, 48, v207
	v_lshl_add_u32 v132, v0, 13, v141
	v_lshlrev_b32_e32 v136, 6, v0
	v_lshl_add_u32 v136, v143, 4, v136
	v_and_b32_e32 v141, 1, v143
	v_lshlrev_b32_e32 v141, 5, v141
	v_lshrrev_b32_e32 v208, 1, v143
	v_lshl_add_u32 v141, v208, 4, v141
	v_lshl_add_u32 v141, v205, 7, v141
	v_add_u32_e32 v0, 0, v207
	v_lshl_add_u32 v209, v0, 13, v141
	v_add_u32_e32 v0, 16, v207
	v_lshl_add_u32 v210, v0, 13, v141
	v_add_u32_e32 v0, 32, v207
	v_lshl_add_u32 v211, v0, 13, v141
	v_add_u32_e32 v0, 48, v207
	v_lshl_add_u32 v212, v0, 13, v141
	v_cmp_gt_u32_e32 vcc, 2, v143
	s_nop 3
	s_mov_b64 s[40:41], vcc
	s_andn2_b64 s[42:43], exec, vcc
	s_bfe_u32 s44, s38, 0x1000a
	s_mov_b32 s0, s91
	s_cmpk_ge_u32 s0, 0xff0
	s_cbranch_scc1 .Lq1_done
	s_lshr_b32 s15, s0, 3
	s_mul_hi_u32 s2, s15, 0xf0f0f0f1
	s_lshr_b32 s2, s2, 4
	s_mul_i32 s1, s2, 136
	s_sub_u32 s1, s0, s1
	s_sub_u32 s2, 29, s2
	s_cmp_eq_u32 s2, 29
	s_cselect_b32 s14, 1, 0
	s_lshl_b32 s15, s1, 18
	s_add_u32 s15, s15, 0x1a40000
	s_add_u32 s4, s26, s15
	s_addc_u32 s5, s27, 0
	s_lshl_b32 s15, s2, 18
	s_add_u32 s6, s26, s15
	s_addc_u32 s7, s27, 0
	s_barrier
	s_add_i32 m0, s38, 0x0
	s_nop 0
	global_load_lds_dwordx4 v114, s[4:5]
	s_add_i32 m0, s38, 0x4000
	s_nop 0
	global_load_lds_dwordx4 v114, s[6:7]
	s_add_i32 m0, s38, 0x1000
	s_nop 0
	global_load_lds_dwordx4 v115, s[4:5]
	s_add_i32 m0, s38, 0x5000
	s_nop 0
	global_load_lds_dwordx4 v115, s[6:7]
	s_add_i32 m0, s38, 0x2000
	s_nop 0
	global_load_lds_dwordx4 v116, s[4:5]
	s_add_i32 m0, s38, 0x6000
	s_nop 0
	global_load_lds_dwordx4 v116, s[6:7]
	s_add_i32 m0, s38, 0x3000
	s_nop 0
	global_load_lds_dwordx4 v117, s[4:5]
	s_add_i32 m0, s38, 0x7000
	s_nop 0
	global_load_lds_dwordx4 v117, s[6:7]
	s_cmp_eq_u32 s14, 1
	s_cbranch_scc0 .Lq1_nx0
	s_cmpk_lt_u32 s38, 0x800
	s_cbranch_scc0 .Lq1_nx0
	s_add_i32 m0, s38, 0x8000
	s_nop 0
	global_load_lds_dwordx4 v118, s[6:7]

.Lq1_task:
	s_lshr_b32 s15, s0, 3
	s_mul_hi_u32 s2, s15, 0xf0f0f0f1
	s_lshr_b32 s2, s2, 4
	s_mul_i32 s1, s2, 136
	s_sub_u32 s1, s0, s1
	s_sub_u32 s2, 29, s2
	s_cmp_eq_u32 s2, 29
	s_cselect_b32 s13, 1, 0
	s_mov_b32 s12, s2
	s_lshl_b32 s15, s1, 20
	s_lshl_b32 s45, s2, 8
	s_add_u32 s15, s15, s45
	s_add_u32 s15, s15, 0x3c40000
	s_add_u32 s8, s26, s15
	s_addc_u32 s9, s27, 0
	s_lshl_b32 s15, s1, 13
	s_add_u32 s15, s15, 0xf740000
	s_add_u32 s10, s26, s15
	s_addc_u32 s11, s27, 0
	v_mov_b32_e32 v2, 0
	v_mov_b32_e32 v3, 0
	v_mov_b32_e32 v4, 0
	v_mov_b32_e32 v5, 0
	v_mov_b32_e32 v6, 0
	v_mov_b32_e32 v7, 0
	v_mov_b32_e32 v8, 0
	v_mov_b32_e32 v9, 0
	v_mov_b32_e32 v10, 0
	v_mov_b32_e32 v11, 0
	v_mov_b32_e32 v12, 0
	v_mov_b32_e32 v13, 0
	v_mov_b32_e32 v14, 0
	v_mov_b32_e32 v15, 0
	v_mov_b32_e32 v16, 0
	v_mov_b32_e32 v17, 0
	v_mov_b32_e32 v18, 0
	v_mov_b32_e32 v19, 0
	v_mov_b32_e32 v20, 0
	v_mov_b32_e32 v21, 0
	v_mov_b32_e32 v22, 0
	v_mov_b32_e32 v23, 0
	v_mov_b32_e32 v24, 0
	v_mov_b32_e32 v25, 0
	v_mov_b32_e32 v26, 0
	v_mov_b32_e32 v27, 0
	v_mov_b32_e32 v28, 0
	v_mov_b32_e32 v29, 0
	v_mov_b32_e32 v30, 0
	v_mov_b32_e32 v31, 0
	v_mov_b32_e32 v32, 0
	v_mov_b32_e32 v33, 0
	v_mov_b32_e32 v34, 0
	v_mov_b32_e32 v35, 0
	v_mov_b32_e32 v36, 0
	v_mov_b32_e32 v37, 0
	v_mov_b32_e32 v38, 0
	v_mov_b32_e32 v39, 0
	v_mov_b32_e32 v40, 0
	v_mov_b32_e32 v41, 0
	v_mov_b32_e32 v42, 0
	v_mov_b32_e32 v43, 0
	v_mov_b32_e32 v44, 0
	v_mov_b32_e32 v45, 0
	v_mov_b32_e32 v46, 0
	v_mov_b32_e32 v47, 0
	v_mov_b32_e32 v48, 0
	v_mov_b32_e32 v49, 0
	v_mov_b32_e32 v50, 0
	v_mov_b32_e32 v51, 0
	v_mov_b32_e32 v52, 0
	v_mov_b32_e32 v53, 0
	v_mov_b32_e32 v54, 0
	v_mov_b32_e32 v55, 0
	v_mov_b32_e32 v56, 0
	v_mov_b32_e32 v57, 0
	v_mov_b32_e32 v58, 0
	v_mov_b32_e32 v59, 0
	v_mov_b32_e32 v60, 0
	v_mov_b32_e32 v61, 0
	v_mov_b32_e32 v62, 0
	v_mov_b32_e32 v63, 0
	v_mov_b32_e32 v64, 0
	v_mov_b32_e32 v65, 0
	v_mov_b32_e32 v66, 0
	v_mov_b32_e32 v67, 0
	v_mov_b32_e32 v68, 0
	v_mov_b32_e32 v69, 0
	v_mov_b32_e32 v70, 0
	v_mov_b32_e32 v71, 0
	v_mov_b32_e32 v72, 0
	v_mov_b32_e32 v73, 0
	v_mov_b32_e32 v74, 0
	v_mov_b32_e32 v75, 0
	v_mov_b32_e32 v76, 0
	v_mov_b32_e32 v77, 0
	v_mov_b32_e32 v78, 0
	v_mov_b32_e32 v79, 0
	v_mov_b32_e32 v80, 0
	v_mov_b32_e32 v81, 0
	s_mov_b32 s39, 0

.Lq1_y7:
	s_add_u32 s39, s39, 1
	s_cmpk_lt_u32 s39, 8
	s_cbranch_scc1 .Lq1_kloop
	s_add_u32 s47, s0, s96
	s_cmpk_ge_u32 s47, 0xff0
	s_cbranch_scc1 .Lq1_nonext
	s_lshr_b32 s15, s47, 3
	s_mul_hi_u32 s2, s15, 0xf0f0f0f1
	s_lshr_b32 s2, s2, 4
	s_mul_i32 s1, s2, 136
	s_sub_u32 s1, s47, s1
	s_sub_u32 s2, 29, s2
	s_cmp_eq_u32 s2, 29
	s_cselect_b32 s14, 1, 0
	s_lshl_b32 s15, s1, 18
	s_add_u32 s15, s15, 0x1a40000
	s_add_u32 s4, s26, s15
	s_addc_u32 s5, s27, 0
	s_lshl_b32 s15, s2, 18
	s_add_u32 s6, s26, s15
	s_addc_u32 s7, s27, 0
	s_add_i32 m0, s38, 0x0
	s_nop 0
	global_load_lds_dwordx4 v114, s[4:5]
	s_add_i32 m0, s38, 0x4000
	s_nop 0
	global_load_lds_dwordx4 v114, s[6:7]
	s_add_i32 m0, s38, 0x1000
	s_nop 0
	global_load_lds_dwordx4 v115, s[4:5]
	s_add_i32 m0, s38, 0x5000
	s_nop 0
	global_load_lds_dwordx4 v115, s[6:7]
	s_add_i32 m0, s38, 0x2000
	s_nop 0
	global_load_lds_dwordx4 v116, s[4:5]
	s_add_i32 m0, s38, 0x6000
	s_nop 0
	global_load_lds_dwordx4 v116, s[6:7]
	s_add_i32 m0, s38, 0x3000
	s_nop 0
	global_load_lds_dwordx4 v117, s[4:5]
	s_add_i32 m0, s38, 0x7000
	s_nop 0
	global_load_lds_dwordx4 v117, s[6:7]
	s_cmp_eq_u32 s14, 1
	s_cbranch_scc0 .Lq1_nx8
	s_cmpk_lt_u32 s38, 0x800
	s_cbranch_scc0 .Lq1_nx8
	s_add_i32 m0, s38, 0x8000
	s_nop 0
	global_load_lds_dwordx4 v118, s[6:7]
